# adaLN step of phase 0 hand-scheduled: silu staging loads issued together, w rows streamed with 48 loads in flight (counted vmcnt); plus rcp divisions in gelu/sigmoid epilogues
# speedup vs baseline: 1.0104x; 1.0023x over previous
.LBB0_45:
	s_barrier
	global_load_dwordx2 v[2:3], v1, s[96:97] offset:80 sc0
	global_load_dwordx2 v[4:5], v1, s[96:97] offset:88 sc0
	global_load_dwordx2 v[6:7], v1, s[96:97] offset:16 sc0
	global_load_dwordx2 v[8:9], v1, s[96:97] offset:56 sc0
	s_and_b32 s0, s93, 0xffffffc0
	v_readlane_b32 s1, v246, 6
	s_cmpk_gt_i32 s1, 0xbf
	v_add_u32_e32 v160, s0, v163
	s_waitcnt vmcnt(3)
	v_readfirstlane_b32 s1, v3
	v_readfirstlane_b32 s0, v2
	s_waitcnt vmcnt(2)
	v_readfirstlane_b32 s13, v5
	v_readfirstlane_b32 s12, v4
	s_waitcnt vmcnt(1)
	v_readfirstlane_b32 s19, v7
	v_readfirstlane_b32 s18, v6
	s_waitcnt vmcnt(0)
	v_readfirstlane_b32 s15, v9
	v_readfirstlane_b32 s14, v8
	s_cbranch_scc1 .LBB0_55
	s_movk_i32 s9, 0x1400
	v_cmp_gt_i32_e32 vcc, s9, v160
	s_and_saveexec_b64 s[16:17], vcc
	s_cbranch_execz .LBB0_49
	s_lshl_b32 s9, s94, 8
	v_ashrrev_i32_e32 v161, 31, v160
	s_add_i32 s9, s9, 0
	s_movk_i32 s20, 0xc000
	v_lshl_add_u64 v[0:1], v[160:161], 2, s[18:19]
	v_lshl_add_u32 v4, v163, 2, s9
	s_mov_b64 s[18:19], 0
	s_movk_i32 s9, 0x1000
	v_mov_b32_e32 v3, 0
	s_mov_b32 s21, -1
	s_mov_b64 s[22:23], 0x800
	s_movk_i32 s24, 0x11ff
	v_mov_b32_e32 v2, v160
	s_mov_b64 s[18:19], 0x1000
	v_lshlrev_b32_e32 v8, 2, v2
	global_load_dword v20, v[0:1], off
	global_load_dword v21, v[0:1], off offset:2048
	v_lshl_add_u64 v[6:7], v[0:1], 0, s[18:19]
	global_load_dword v22, v[6:7], off
	global_load_dword v23, v[6:7], off offset:2048
	v_lshl_add_u64 v[6:7], v[6:7], 0, s[18:19]
	global_load_dword v24, v[6:7], off
	global_load_dword v25, v[6:7], off offset:2048
	v_lshl_add_u64 v[6:7], v[6:7], 0, s[18:19]
	global_load_dword v26, v[6:7], off
	global_load_dword v27, v[6:7], off offset:2048
	global_load_dword v28, v8, s[14:15]
	global_load_dword v29, v8, s[14:15] offset:2048
	s_waitcnt vmcnt(0) lgkmcnt(0)
	v_mul_f32_e32 v30, 0xbfb8aa3b, v20
	v_exp_f32_e32 v30, v30
	s_nop 0
	v_add_f32_e32 v30, 1.0, v30
	v_div_scale_f32 v31, s[26:27], v30, v30, 1.0
	v_rcp_f32_e32 v32, v31
	v_div_scale_f32 v33, vcc, 1.0, v30, 1.0
	v_fma_f32 v34, -v31, v32, 1.0
	v_fmac_f32_e32 v32, v34, v32
	v_mul_f32_e32 v34, v33, v32
	v_fma_f32 v35, -v31, v34, v33
	v_fmac_f32_e32 v34, v35, v32
	v_fma_f32 v31, -v31, v34, v33
	v_div_fmas_f32 v31, v31, v32, v34
	v_div_fixup_f32 v30, v31, v30, 1.0
	v_mul_f32_e32 v20, v20, v30
	ds_write_b32 v4, v20
	v_mul_f32_e32 v38, 0xbfb8aa3b, v21
	v_exp_f32_e32 v38, v38
	s_nop 0
	v_add_f32_e32 v38, 1.0, v38
	v_div_scale_f32 v39, s[26:27], v38, v38, 1.0
	v_rcp_f32_e32 v40, v39
	v_div_scale_f32 v41, vcc, 1.0, v38, 1.0
	v_fma_f32 v42, -v39, v40, 1.0
	v_fmac_f32_e32 v40, v42, v40
	v_mul_f32_e32 v42, v41, v40
	v_fma_f32 v43, -v39, v42, v41
	v_fmac_f32_e32 v42, v43, v40
	v_fma_f32 v39, -v39, v42, v41
	v_div_fmas_f32 v39, v39, v40, v42
	v_div_fixup_f32 v38, v39, v38, 1.0
	v_mul_f32_e32 v21, v21, v38
	ds_write_b32 v4, v21 offset:2048
	v_mul_f32_e32 v46, 0xbfb8aa3b, v22
	v_exp_f32_e32 v46, v46
	s_nop 0
	v_add_f32_e32 v46, 1.0, v46
	v_div_scale_f32 v47, s[26:27], v46, v46, 1.0
	v_rcp_f32_e32 v48, v47
	v_div_scale_f32 v49, vcc, 1.0, v46, 1.0
	v_fma_f32 v50, -v47, v48, 1.0
	v_fmac_f32_e32 v48, v50, v48
	v_mul_f32_e32 v50, v49, v48
	v_fma_f32 v51, -v47, v50, v49
	v_fmac_f32_e32 v50, v51, v48
	v_fma_f32 v47, -v47, v50, v49
	v_div_fmas_f32 v47, v47, v48, v50
	v_div_fixup_f32 v46, v47, v46, 1.0
	v_mul_f32_e32 v22, v22, v46
	ds_write_b32 v4, v22 offset:4096
	v_mul_f32_e32 v54, 0xbfb8aa3b, v23
	v_exp_f32_e32 v54, v54
	s_nop 0
	v_add_f32_e32 v54, 1.0, v54
	v_div_scale_f32 v55, s[26:27], v54, v54, 1.0
	v_rcp_f32_e32 v56, v55
	v_div_scale_f32 v57, vcc, 1.0, v54, 1.0
	v_fma_f32 v58, -v55, v56, 1.0
	v_fmac_f32_e32 v56, v58, v56
	v_mul_f32_e32 v58, v57, v56
	v_fma_f32 v59, -v55, v58, v57
	v_fmac_f32_e32 v58, v59, v56
	v_fma_f32 v55, -v55, v58, v57
	v_div_fmas_f32 v55, v55, v56, v58
	v_div_fixup_f32 v54, v55, v54, 1.0
	v_mul_f32_e32 v23, v23, v54
	ds_write_b32 v4, v23 offset:6144
	v_mul_f32_e32 v62, 0xbfb8aa3b, v24
	v_exp_f32_e32 v62, v62
	s_nop 0
	v_add_f32_e32 v62, 1.0, v62
	v_div_scale_f32 v63, s[26:27], v62, v62, 1.0
	v_rcp_f32_e32 v64, v63
	v_div_scale_f32 v65, vcc, 1.0, v62, 1.0
	v_fma_f32 v66, -v63, v64, 1.0
	v_fmac_f32_e32 v64, v66, v64
	v_mul_f32_e32 v66, v65, v64
	v_fma_f32 v67, -v63, v66, v65
	v_fmac_f32_e32 v66, v67, v64
	v_fma_f32 v63, -v63, v66, v65
	v_div_fmas_f32 v63, v63, v64, v66
	v_div_fixup_f32 v62, v63, v62, 1.0
	v_mul_f32_e32 v24, v24, v62
	ds_write_b32 v4, v24 offset:8192
	v_mul_f32_e32 v70, 0xbfb8aa3b, v25
	v_exp_f32_e32 v70, v70
	s_nop 0
	v_add_f32_e32 v70, 1.0, v70
	v_div_scale_f32 v71, s[26:27], v70, v70, 1.0
	v_rcp_f32_e32 v72, v71
	v_div_scale_f32 v73, vcc, 1.0, v70, 1.0
	v_fma_f32 v74, -v71, v72, 1.0
	v_fmac_f32_e32 v72, v74, v72
	v_mul_f32_e32 v74, v73, v72
	v_fma_f32 v75, -v71, v74, v73
	v_fmac_f32_e32 v74, v75, v72
	v_fma_f32 v71, -v71, v74, v73
	v_div_fmas_f32 v71, v71, v72, v74
	v_div_fixup_f32 v70, v71, v70, 1.0
	v_mul_f32_e32 v25, v25, v70
	ds_write_b32 v4, v25 offset:10240
	v_mul_f32_e32 v78, 0xbfb8aa3b, v26
	v_exp_f32_e32 v78, v78
	s_nop 0
	v_add_f32_e32 v78, 1.0, v78
	v_div_scale_f32 v79, s[26:27], v78, v78, 1.0
	v_rcp_f32_e32 v80, v79
	v_div_scale_f32 v81, vcc, 1.0, v78, 1.0
	v_fma_f32 v82, -v79, v80, 1.0
	v_fmac_f32_e32 v80, v82, v80
	v_mul_f32_e32 v82, v81, v80
	v_fma_f32 v83, -v79, v82, v81
	v_fmac_f32_e32 v82, v83, v80
	v_fma_f32 v79, -v79, v82, v81
	v_div_fmas_f32 v79, v79, v80, v82
	v_div_fixup_f32 v78, v79, v78, 1.0
	v_mul_f32_e32 v26, v26, v78
	ds_write_b32 v4, v26 offset:12288
	v_mul_f32_e32 v86, 0xbfb8aa3b, v27
	v_exp_f32_e32 v86, v86
	s_nop 0
	v_add_f32_e32 v86, 1.0, v86
	v_div_scale_f32 v87, s[26:27], v86, v86, 1.0
	v_rcp_f32_e32 v88, v87
	v_div_scale_f32 v89, vcc, 1.0, v86, 1.0
	v_fma_f32 v90, -v87, v88, 1.0
	v_fmac_f32_e32 v88, v90, v88
	v_mul_f32_e32 v90, v89, v88
	v_fma_f32 v91, -v87, v90, v89
	v_fmac_f32_e32 v90, v91, v88
	v_fma_f32 v87, -v87, v90, v89
	v_div_fmas_f32 v87, v87, v88, v90
	v_div_fixup_f32 v86, v87, v86, 1.0
	v_mul_f32_e32 v27, v27, v86
	ds_write_b32 v4, v27 offset:14336
	v_mul_f32_e32 v94, 0xbfb8aa3b, v28
	v_exp_f32_e32 v94, v94
	s_nop 0
	v_add_f32_e32 v94, 1.0, v94
	v_div_scale_f32 v95, s[26:27], v94, v94, 1.0
	v_rcp_f32_e32 v96, v95
	v_div_scale_f32 v97, vcc, 1.0, v94, 1.0
	v_fma_f32 v98, -v95, v96, 1.0
	v_fmac_f32_e32 v96, v98, v96
	v_mul_f32_e32 v98, v97, v96
	v_fma_f32 v99, -v95, v98, v97
	v_fmac_f32_e32 v98, v99, v96
	v_fma_f32 v95, -v95, v98, v97
	v_div_fmas_f32 v95, v95, v96, v98
	v_div_fixup_f32 v94, v95, v94, 1.0
	v_mul_f32_e32 v28, v28, v94
	ds_write_b32 v4, v28 offset:16384
	v_mul_f32_e32 v102, 0xbfb8aa3b, v29
	v_exp_f32_e32 v102, v102
	s_nop 0
	v_add_f32_e32 v102, 1.0, v102
	v_div_scale_f32 v103, s[26:27], v102, v102, 1.0
	v_rcp_f32_e32 v104, v103
	v_div_scale_f32 v105, vcc, 1.0, v102, 1.0
	v_fma_f32 v106, -v103, v104, 1.0
	v_fmac_f32_e32 v104, v106, v104
	v_mul_f32_e32 v106, v105, v104
	v_fma_f32 v107, -v103, v106, v105
	v_fmac_f32_e32 v106, v107, v104
	v_fma_f32 v103, -v103, v106, v105
	v_div_fmas_f32 v103, v103, v104, v106
	v_div_fixup_f32 v102, v103, v102, 1.0
	v_mul_f32_e32 v29, v29, v102
	ds_write_b32 v4, v29 offset:18432

.LBB0_51:
	s_mul_hi_i32 s0, s62, 0x2aaaaaab
	s_lshr_b32 s1, s0, 31
	s_ashr_i32 s63, s0, 4
	s_add_i32 s63, s63, s1
	s_mul_i32 s0, s63, 0x60
	s_sub_i32 s0, s62, s0
	v_lshl_or_b32 v168, s0, 6, v161
	v_mad_i64_i32 v[0:1], s[0:1], s63, v167, v[164:165]
	v_ashrrev_i32_e32 v169, 31, v168
	v_lshl_add_u64 v[170:171], v[168:169], 2, v[0:1]
	v_mov_b32_e32 v169, 0
	s_mov_b64 s[14:15], 0
	v_mov_b32_e32 v180, v178
	v_mov_b32_e32 v172, 0
	v_mov_b32_e32 v173, v169
	v_mov_b32_e32 v174, 0
	v_mov_b32_e32 v175, v169
	v_readfirstlane_b32 s0, v170
	v_readfirstlane_b32 s1, v171
	s_nop 1
	v_subrev_u32_e32 v176, s0, v170
	s_nop 3
	global_load_dword v0, v176, s[0:1]
	s_add_u32 s0, s0, 0x6000
	s_addc_u32 s1, s1, 0
	global_load_dword v1, v176, s[0:1]
	s_add_u32 s0, s0, 0x6000
	s_addc_u32 s1, s1, 0
	global_load_dword v2, v176, s[0:1]
	s_add_u32 s0, s0, 0x6000
	s_addc_u32 s1, s1, 0
	global_load_dword v3, v176, s[0:1]
	s_add_u32 s0, s0, 0x6000
	s_addc_u32 s1, s1, 0
	global_load_dword v4, v176, s[0:1]
	s_add_u32 s0, s0, 0x6000
	s_addc_u32 s1, s1, 0
	global_load_dword v5, v176, s[0:1]
	s_add_u32 s0, s0, 0x6000
	s_addc_u32 s1, s1, 0
	global_load_dword v6, v176, s[0:1]
	s_add_u32 s0, s0, 0x6000
	s_addc_u32 s1, s1, 0
	global_load_dword v7, v176, s[0:1]
	s_add_u32 s0, s0, 0x6000
	s_addc_u32 s1, s1, 0
	global_load_dword v8, v176, s[0:1]
	s_add_u32 s0, s0, 0x6000
	s_addc_u32 s1, s1, 0
	global_load_dword v9, v176, s[0:1]
	s_add_u32 s0, s0, 0x6000
	s_addc_u32 s1, s1, 0
	global_load_dword v10, v176, s[0:1]
	s_add_u32 s0, s0, 0x6000
	s_addc_u32 s1, s1, 0
	global_load_dword v11, v176, s[0:1]
	s_add_u32 s0, s0, 0x6000
	s_addc_u32 s1, s1, 0
	global_load_dword v12, v176, s[0:1]
	s_add_u32 s0, s0, 0x6000
	s_addc_u32 s1, s1, 0
	global_load_dword v13, v176, s[0:1]
	s_add_u32 s0, s0, 0x6000
	s_addc_u32 s1, s1, 0
	global_load_dword v14, v176, s[0:1]
	s_add_u32 s0, s0, 0x6000
	s_addc_u32 s1, s1, 0
	global_load_dword v15, v176, s[0:1]
	s_add_u32 s0, s0, 0x6000
	s_addc_u32 s1, s1, 0
	global_load_dword v16, v176, s[0:1]
	s_add_u32 s0, s0, 0x6000
	s_addc_u32 s1, s1, 0
	global_load_dword v17, v176, s[0:1]
	s_add_u32 s0, s0, 0x6000
	s_addc_u32 s1, s1, 0
	global_load_dword v18, v176, s[0:1]
	s_add_u32 s0, s0, 0x6000
	s_addc_u32 s1, s1, 0
	global_load_dword v19, v176, s[0:1]
	s_add_u32 s0, s0, 0x6000
	s_addc_u32 s1, s1, 0
	global_load_dword v20, v176, s[0:1]
	s_add_u32 s0, s0, 0x6000
	s_addc_u32 s1, s1, 0
	global_load_dword v21, v176, s[0:1]
	s_add_u32 s0, s0, 0x6000
	s_addc_u32 s1, s1, 0
	global_load_dword v22, v176, s[0:1]
	s_add_u32 s0, s0, 0x6000
	s_addc_u32 s1, s1, 0
	global_load_dword v23, v176, s[0:1]
	s_add_u32 s0, s0, 0x6000
	s_addc_u32 s1, s1, 0
	global_load_dword v24, v176, s[0:1]
	s_add_u32 s0, s0, 0x6000
	s_addc_u32 s1, s1, 0
	global_load_dword v25, v176, s[0:1]
	s_add_u32 s0, s0, 0x6000
	s_addc_u32 s1, s1, 0
	global_load_dword v26, v176, s[0:1]
	s_add_u32 s0, s0, 0x6000
	s_addc_u32 s1, s1, 0
	global_load_dword v27, v176, s[0:1]
	s_add_u32 s0, s0, 0x6000
	s_addc_u32 s1, s1, 0
	global_load_dword v28, v176, s[0:1]
	s_add_u32 s0, s0, 0x6000
	s_addc_u32 s1, s1, 0
	global_load_dword v29, v176, s[0:1]
	s_add_u32 s0, s0, 0x6000
	s_addc_u32 s1, s1, 0
	global_load_dword v30, v176, s[0:1]
	s_add_u32 s0, s0, 0x6000
	s_addc_u32 s1, s1, 0
	global_load_dword v31, v176, s[0:1]
	s_add_u32 s0, s0, 0x6000
	s_addc_u32 s1, s1, 0
	global_load_dword v32, v176, s[0:1]
	s_add_u32 s0, s0, 0x6000
	s_addc_u32 s1, s1, 0
	global_load_dword v33, v176, s[0:1]
	s_add_u32 s0, s0, 0x6000
	s_addc_u32 s1, s1, 0
	global_load_dword v34, v176, s[0:1]
	s_add_u32 s0, s0, 0x6000
	s_addc_u32 s1, s1, 0
	global_load_dword v35, v176, s[0:1]
	s_add_u32 s0, s0, 0x6000
	s_addc_u32 s1, s1, 0
	global_load_dword v36, v176, s[0:1]
	s_add_u32 s0, s0, 0x6000
	s_addc_u32 s1, s1, 0
	global_load_dword v37, v176, s[0:1]
	s_add_u32 s0, s0, 0x6000
	s_addc_u32 s1, s1, 0
	global_load_dword v38, v176, s[0:1]
	s_add_u32 s0, s0, 0x6000
	s_addc_u32 s1, s1, 0
	global_load_dword v39, v176, s[0:1]
	s_add_u32 s0, s0, 0x6000
	s_addc_u32 s1, s1, 0
	global_load_dword v40, v176, s[0:1]
	s_add_u32 s0, s0, 0x6000
	s_addc_u32 s1, s1, 0
	global_load_dword v41, v176, s[0:1]
	s_add_u32 s0, s0, 0x6000
	s_addc_u32 s1, s1, 0
	global_load_dword v42, v176, s[0:1]
	s_add_u32 s0, s0, 0x6000
	s_addc_u32 s1, s1, 0
	global_load_dword v43, v176, s[0:1]
	s_add_u32 s0, s0, 0x6000
	s_addc_u32 s1, s1, 0
	global_load_dword v44, v176, s[0:1]
	s_add_u32 s0, s0, 0x6000
	s_addc_u32 s1, s1, 0
	global_load_dword v45, v176, s[0:1]
	s_add_u32 s0, s0, 0x6000
	s_addc_u32 s1, s1, 0
	global_load_dword v46, v176, s[0:1]
	s_add_u32 s0, s0, 0x6000
	s_addc_u32 s1, s1, 0
	global_load_dword v47, v176, s[0:1]
	s_add_u32 s0, s0, 0x6000
	s_addc_u32 s1, s1, 0
	ds_read_b128 v[64:67], v180
	ds_read_b128 v[68:71], v180 offset:16
	ds_read_b128 v[72:75], v180 offset:32
	ds_read_b128 v[76:79], v180 offset:48
	ds_read_b128 v[80:83], v180 offset:4096
	ds_read_b128 v[84:87], v180 offset:4112
	ds_read_b128 v[88:91], v180 offset:4128
	ds_read_b128 v[92:95], v180 offset:4144
	ds_read_b128 v[96:99], v180 offset:8192
	ds_read_b128 v[100:103], v180 offset:8208
	ds_read_b128 v[104:107], v180 offset:8224
	ds_read_b128 v[108:111], v180 offset:8240
	ds_read_b128 v[112:115], v180 offset:12288
	ds_read_b128 v[116:119], v180 offset:12304
	ds_read_b128 v[120:123], v180 offset:12320
	ds_read_b128 v[124:127], v180 offset:12336
	ds_read_b128 v[128:131], v180 offset:16384
	ds_read_b128 v[132:135], v180 offset:16400
	ds_read_b128 v[136:139], v180 offset:16416
	ds_read_b128 v[140:143], v180 offset:16432
	s_waitcnt vmcnt(32)
	global_load_dword v48, v176, s[0:1]
	s_add_u32 s0, s0, 0x6000
	s_addc_u32 s1, s1, 0
	global_load_dword v49, v176, s[0:1]
	s_add_u32 s0, s0, 0x6000
	s_addc_u32 s1, s1, 0
	global_load_dword v50, v176, s[0:1]
	s_add_u32 s0, s0, 0x6000
	s_addc_u32 s1, s1, 0
	global_load_dword v51, v176, s[0:1]
	s_add_u32 s0, s0, 0x6000
	s_addc_u32 s1, s1, 0
	global_load_dword v52, v176, s[0:1]
	s_add_u32 s0, s0, 0x6000
	s_addc_u32 s1, s1, 0
	global_load_dword v53, v176, s[0:1]
	s_add_u32 s0, s0, 0x6000
	s_addc_u32 s1, s1, 0
	global_load_dword v54, v176, s[0:1]
	s_add_u32 s0, s0, 0x6000
	s_addc_u32 s1, s1, 0
	global_load_dword v55, v176, s[0:1]
	s_add_u32 s0, s0, 0x6000
	s_addc_u32 s1, s1, 0
	global_load_dword v56, v176, s[0:1]
	s_add_u32 s0, s0, 0x6000
	s_addc_u32 s1, s1, 0
	global_load_dword v57, v176, s[0:1]
	s_add_u32 s0, s0, 0x6000
	s_addc_u32 s1, s1, 0
	global_load_dword v58, v176, s[0:1]
	s_add_u32 s0, s0, 0x6000
	s_addc_u32 s1, s1, 0
	global_load_dword v59, v176, s[0:1]
	s_add_u32 s0, s0, 0x6000
	s_addc_u32 s1, s1, 0
	global_load_dword v60, v176, s[0:1]
	s_add_u32 s0, s0, 0x6000
	s_addc_u32 s1, s1, 0
	global_load_dword v61, v176, s[0:1]
	s_add_u32 s0, s0, 0x6000
	s_addc_u32 s1, s1, 0
	global_load_dword v62, v176, s[0:1]
	s_add_u32 s0, s0, 0x6000
	s_addc_u32 s1, s1, 0
	global_load_dword v63, v176, s[0:1]
	s_add_u32 s0, s0, 0x6000
	s_addc_u32 s1, s1, 0
	s_waitcnt lgkmcnt(0)
	v_fmac_f32_e32 v172, v0, v64
	v_fmac_f32_e32 v173, v0, v80
	v_fmac_f32_e32 v174, v0, v96
	v_fmac_f32_e32 v175, v0, v112
	v_fmac_f32_e32 v169, v0, v128
	v_fmac_f32_e32 v172, v1, v65
	v_fmac_f32_e32 v173, v1, v81
	v_fmac_f32_e32 v174, v1, v97
	v_fmac_f32_e32 v175, v1, v113
	v_fmac_f32_e32 v169, v1, v129
	v_fmac_f32_e32 v172, v2, v66
	v_fmac_f32_e32 v173, v2, v82
	v_fmac_f32_e32 v174, v2, v98
	v_fmac_f32_e32 v175, v2, v114
	v_fmac_f32_e32 v169, v2, v130
	v_fmac_f32_e32 v172, v3, v67
	v_fmac_f32_e32 v173, v3, v83
	v_fmac_f32_e32 v174, v3, v99
	v_fmac_f32_e32 v175, v3, v115
	v_fmac_f32_e32 v169, v3, v131
	v_fmac_f32_e32 v172, v4, v68
	v_fmac_f32_e32 v173, v4, v84
	v_fmac_f32_e32 v174, v4, v100
	v_fmac_f32_e32 v175, v4, v116
	v_fmac_f32_e32 v169, v4, v132
	v_fmac_f32_e32 v172, v5, v69
	v_fmac_f32_e32 v173, v5, v85
	v_fmac_f32_e32 v174, v5, v101
	v_fmac_f32_e32 v175, v5, v117
	v_fmac_f32_e32 v169, v5, v133
	v_fmac_f32_e32 v172, v6, v70
	v_fmac_f32_e32 v173, v6, v86
	v_fmac_f32_e32 v174, v6, v102
	v_fmac_f32_e32 v175, v6, v118
	v_fmac_f32_e32 v169, v6, v134
	v_fmac_f32_e32 v172, v7, v71
	v_fmac_f32_e32 v173, v7, v87
	v_fmac_f32_e32 v174, v7, v103
	v_fmac_f32_e32 v175, v7, v119
	v_fmac_f32_e32 v169, v7, v135
	v_fmac_f32_e32 v172, v8, v72
	v_fmac_f32_e32 v173, v8, v88
	v_fmac_f32_e32 v174, v8, v104
	v_fmac_f32_e32 v175, v8, v120
	v_fmac_f32_e32 v169, v8, v136
	v_fmac_f32_e32 v172, v9, v73
	v_fmac_f32_e32 v173, v9, v89
	v_fmac_f32_e32 v174, v9, v105
	v_fmac_f32_e32 v175, v9, v121
	v_fmac_f32_e32 v169, v9, v137
	v_fmac_f32_e32 v172, v10, v74
	v_fmac_f32_e32 v173, v10, v90
	v_fmac_f32_e32 v174, v10, v106
	v_fmac_f32_e32 v175, v10, v122
	v_fmac_f32_e32 v169, v10, v138
	v_fmac_f32_e32 v172, v11, v75
	v_fmac_f32_e32 v173, v11, v91
	v_fmac_f32_e32 v174, v11, v107
	v_fmac_f32_e32 v175, v11, v123
	v_fmac_f32_e32 v169, v11, v139
	v_fmac_f32_e32 v172, v12, v76
	v_fmac_f32_e32 v173, v12, v92
	v_fmac_f32_e32 v174, v12, v108
	v_fmac_f32_e32 v175, v12, v124
	v_fmac_f32_e32 v169, v12, v140
	v_fmac_f32_e32 v172, v13, v77
	v_fmac_f32_e32 v173, v13, v93
	v_fmac_f32_e32 v174, v13, v109
	v_fmac_f32_e32 v175, v13, v125
	v_fmac_f32_e32 v169, v13, v141
	v_fmac_f32_e32 v172, v14, v78
	v_fmac_f32_e32 v173, v14, v94
	v_fmac_f32_e32 v174, v14, v110
	v_fmac_f32_e32 v175, v14, v126
	v_fmac_f32_e32 v169, v14, v142
	v_fmac_f32_e32 v172, v15, v79
	v_fmac_f32_e32 v173, v15, v95
	v_fmac_f32_e32 v174, v15, v111
	v_fmac_f32_e32 v175, v15, v127
	v_fmac_f32_e32 v169, v15, v143
	ds_read_b128 v[64:67], v180 offset:64
	ds_read_b128 v[68:71], v180 offset:80
	ds_read_b128 v[72:75], v180 offset:96
	ds_read_b128 v[76:79], v180 offset:112
	ds_read_b128 v[80:83], v180 offset:4160
	ds_read_b128 v[84:87], v180 offset:4176
	ds_read_b128 v[88:91], v180 offset:4192
	ds_read_b128 v[92:95], v180 offset:4208
	ds_read_b128 v[96:99], v180 offset:8256
	ds_read_b128 v[100:103], v180 offset:8272
	ds_read_b128 v[104:107], v180 offset:8288
	ds_read_b128 v[108:111], v180 offset:8304
	ds_read_b128 v[112:115], v180 offset:12352
	ds_read_b128 v[116:119], v180 offset:12368
	ds_read_b128 v[120:123], v180 offset:12384
	ds_read_b128 v[124:127], v180 offset:12400
	ds_read_b128 v[128:131], v180 offset:16448
	ds_read_b128 v[132:135], v180 offset:16464
	ds_read_b128 v[136:139], v180 offset:16480
	ds_read_b128 v[140:143], v180 offset:16496
	s_waitcnt vmcnt(32)
	global_load_dword v0, v176, s[0:1]
	s_add_u32 s0, s0, 0x6000
	s_addc_u32 s1, s1, 0
	global_load_dword v1, v176, s[0:1]
	s_add_u32 s0, s0, 0x6000
	s_addc_u32 s1, s1, 0
	global_load_dword v2, v176, s[0:1]
	s_add_u32 s0, s0, 0x6000
	s_addc_u32 s1, s1, 0
	global_load_dword v3, v176, s[0:1]
	s_add_u32 s0, s0, 0x6000
	s_addc_u32 s1, s1, 0
	global_load_dword v4, v176, s[0:1]
	s_add_u32 s0, s0, 0x6000
	s_addc_u32 s1, s1, 0
	global_load_dword v5, v176, s[0:1]
	s_add_u32 s0, s0, 0x6000
	s_addc_u32 s1, s1, 0
	global_load_dword v6, v176, s[0:1]
	s_add_u32 s0, s0, 0x6000
	s_addc_u32 s1, s1, 0
	global_load_dword v7, v176, s[0:1]
	s_add_u32 s0, s0, 0x6000
	s_addc_u32 s1, s1, 0
	global_load_dword v8, v176, s[0:1]
	s_add_u32 s0, s0, 0x6000
	s_addc_u32 s1, s1, 0
	global_load_dword v9, v176, s[0:1]
	s_add_u32 s0, s0, 0x6000
	s_addc_u32 s1, s1, 0
	global_load_dword v10, v176, s[0:1]
	s_add_u32 s0, s0, 0x6000
	s_addc_u32 s1, s1, 0
	global_load_dword v11, v176, s[0:1]
	s_add_u32 s0, s0, 0x6000
	s_addc_u32 s1, s1, 0
	global_load_dword v12, v176, s[0:1]
	s_add_u32 s0, s0, 0x6000
	s_addc_u32 s1, s1, 0
	global_load_dword v13, v176, s[0:1]
	s_add_u32 s0, s0, 0x6000
	s_addc_u32 s1, s1, 0
	global_load_dword v14, v176, s[0:1]
	s_add_u32 s0, s0, 0x6000
	s_addc_u32 s1, s1, 0
	global_load_dword v15, v176, s[0:1]
	s_add_u32 s0, s0, 0x6000
	s_addc_u32 s1, s1, 0
	s_waitcnt lgkmcnt(0)
	v_fmac_f32_e32 v172, v16, v64
	v_fmac_f32_e32 v173, v16, v80
	v_fmac_f32_e32 v174, v16, v96
	v_fmac_f32_e32 v175, v16, v112
	v_fmac_f32_e32 v169, v16, v128
	v_fmac_f32_e32 v172, v17, v65
	v_fmac_f32_e32 v173, v17, v81
	v_fmac_f32_e32 v174, v17, v97
	v_fmac_f32_e32 v175, v17, v113
	v_fmac_f32_e32 v169, v17, v129
	v_fmac_f32_e32 v172, v18, v66
	v_fmac_f32_e32 v173, v18, v82
	v_fmac_f32_e32 v174, v18, v98
	v_fmac_f32_e32 v175, v18, v114
	v_fmac_f32_e32 v169, v18, v130
	v_fmac_f32_e32 v172, v19, v67
	v_fmac_f32_e32 v173, v19, v83
	v_fmac_f32_e32 v174, v19, v99
	v_fmac_f32_e32 v175, v19, v115
	v_fmac_f32_e32 v169, v19, v131
	v_fmac_f32_e32 v172, v20, v68
	v_fmac_f32_e32 v173, v20, v84
	v_fmac_f32_e32 v174, v20, v100
	v_fmac_f32_e32 v175, v20, v116
	v_fmac_f32_e32 v169, v20, v132
	v_fmac_f32_e32 v172, v21, v69
	v_fmac_f32_e32 v173, v21, v85
	v_fmac_f32_e32 v174, v21, v101
	v_fmac_f32_e32 v175, v21, v117
	v_fmac_f32_e32 v169, v21, v133
	v_fmac_f32_e32 v172, v22, v70
	v_fmac_f32_e32 v173, v22, v86
	v_fmac_f32_e32 v174, v22, v102
	v_fmac_f32_e32 v175, v22, v118
	v_fmac_f32_e32 v169, v22, v134
	v_fmac_f32_e32 v172, v23, v71
	v_fmac_f32_e32 v173, v23, v87
	v_fmac_f32_e32 v174, v23, v103
	v_fmac_f32_e32 v175, v23, v119
	v_fmac_f32_e32 v169, v23, v135
	v_fmac_f32_e32 v172, v24, v72
	v_fmac_f32_e32 v173, v24, v88
	v_fmac_f32_e32 v174, v24, v104
	v_fmac_f32_e32 v175, v24, v120
	v_fmac_f32_e32 v169, v24, v136
	v_fmac_f32_e32 v172, v25, v73
	v_fmac_f32_e32 v173, v25, v89
	v_fmac_f32_e32 v174, v25, v105
	v_fmac_f32_e32 v175, v25, v121
	v_fmac_f32_e32 v169, v25, v137
	v_fmac_f32_e32 v172, v26, v74
	v_fmac_f32_e32 v173, v26, v90
	v_fmac_f32_e32 v174, v26, v106
	v_fmac_f32_e32 v175, v26, v122
	v_fmac_f32_e32 v169, v26, v138
	v_fmac_f32_e32 v172, v27, v75
	v_fmac_f32_e32 v173, v27, v91
	v_fmac_f32_e32 v174, v27, v107
	v_fmac_f32_e32 v175, v27, v123
	v_fmac_f32_e32 v169, v27, v139
	v_fmac_f32_e32 v172, v28, v76
	v_fmac_f32_e32 v173, v28, v92
	v_fmac_f32_e32 v174, v28, v108
	v_fmac_f32_e32 v175, v28, v124
	v_fmac_f32_e32 v169, v28, v140
	v_fmac_f32_e32 v172, v29, v77
	v_fmac_f32_e32 v173, v29, v93
	v_fmac_f32_e32 v174, v29, v109
	v_fmac_f32_e32 v175, v29, v125
	v_fmac_f32_e32 v169, v29, v141
	v_fmac_f32_e32 v172, v30, v78
	v_fmac_f32_e32 v173, v30, v94
	v_fmac_f32_e32 v174, v30, v110
	v_fmac_f32_e32 v175, v30, v126
	v_fmac_f32_e32 v169, v30, v142
	v_fmac_f32_e32 v172, v31, v79
	v_fmac_f32_e32 v173, v31, v95
	v_fmac_f32_e32 v174, v31, v111
	v_fmac_f32_e32 v175, v31, v127
	v_fmac_f32_e32 v169, v31, v143
	ds_read_b128 v[64:67], v180 offset:128
	ds_read_b128 v[68:71], v180 offset:144
	ds_read_b128 v[72:75], v180 offset:160
	ds_read_b128 v[76:79], v180 offset:176
	ds_read_b128 v[80:83], v180 offset:4224
	ds_read_b128 v[84:87], v180 offset:4240
	ds_read_b128 v[88:91], v180 offset:4256
	ds_read_b128 v[92:95], v180 offset:4272
	ds_read_b128 v[96:99], v180 offset:8320
	ds_read_b128 v[100:103], v180 offset:8336
	ds_read_b128 v[104:107], v180 offset:8352
	ds_read_b128 v[108:111], v180 offset:8368
	ds_read_b128 v[112:115], v180 offset:12416
	ds_read_b128 v[116:119], v180 offset:12432
	ds_read_b128 v[120:123], v180 offset:12448
	ds_read_b128 v[124:127], v180 offset:12464
	ds_read_b128 v[128:131], v180 offset:16512
	ds_read_b128 v[132:135], v180 offset:16528
	ds_read_b128 v[136:139], v180 offset:16544
	ds_read_b128 v[140:143], v180 offset:16560
	s_waitcnt vmcnt(32)
	global_load_dword v16, v176, s[0:1]
	s_add_u32 s0, s0, 0x6000
	s_addc_u32 s1, s1, 0
	global_load_dword v17, v176, s[0:1]
	s_add_u32 s0, s0, 0x6000
	s_addc_u32 s1, s1, 0
	global_load_dword v18, v176, s[0:1]
	s_add_u32 s0, s0, 0x6000
	s_addc_u32 s1, s1, 0
	global_load_dword v19, v176, s[0:1]
	s_add_u32 s0, s0, 0x6000
	s_addc_u32 s1, s1, 0
	global_load_dword v20, v176, s[0:1]
	s_add_u32 s0, s0, 0x6000
	s_addc_u32 s1, s1, 0
	global_load_dword v21, v176, s[0:1]
	s_add_u32 s0, s0, 0x6000
	s_addc_u32 s1, s1, 0
	global_load_dword v22, v176, s[0:1]
	s_add_u32 s0, s0, 0x6000
	s_addc_u32 s1, s1, 0
	global_load_dword v23, v176, s[0:1]
	s_add_u32 s0, s0, 0x6000
	s_addc_u32 s1, s1, 0
	global_load_dword v24, v176, s[0:1]
	s_add_u32 s0, s0, 0x6000
	s_addc_u32 s1, s1, 0
	global_load_dword v25, v176, s[0:1]
	s_add_u32 s0, s0, 0x6000
	s_addc_u32 s1, s1, 0
	global_load_dword v26, v176, s[0:1]
	s_add_u32 s0, s0, 0x6000
	s_addc_u32 s1, s1, 0
	global_load_dword v27, v176, s[0:1]
	s_add_u32 s0, s0, 0x6000
	s_addc_u32 s1, s1, 0
	global_load_dword v28, v176, s[0:1]
	s_add_u32 s0, s0, 0x6000
	s_addc_u32 s1, s1, 0
	global_load_dword v29, v176, s[0:1]
	s_add_u32 s0, s0, 0x6000
	s_addc_u32 s1, s1, 0
	global_load_dword v30, v176, s[0:1]
	s_add_u32 s0, s0, 0x6000
	s_addc_u32 s1, s1, 0
	global_load_dword v31, v176, s[0:1]
	s_add_u32 s0, s0, 0x6000
	s_addc_u32 s1, s1, 0
	s_waitcnt lgkmcnt(0)
	v_fmac_f32_e32 v172, v32, v64
	v_fmac_f32_e32 v173, v32, v80
	v_fmac_f32_e32 v174, v32, v96
	v_fmac_f32_e32 v175, v32, v112
	v_fmac_f32_e32 v169, v32, v128
	v_fmac_f32_e32 v172, v33, v65
	v_fmac_f32_e32 v173, v33, v81
	v_fmac_f32_e32 v174, v33, v97
	v_fmac_f32_e32 v175, v33, v113
	v_fmac_f32_e32 v169, v33, v129
	v_fmac_f32_e32 v172, v34, v66
	v_fmac_f32_e32 v173, v34, v82
	v_fmac_f32_e32 v174, v34, v98
	v_fmac_f32_e32 v175, v34, v114
	v_fmac_f32_e32 v169, v34, v130
	v_fmac_f32_e32 v172, v35, v67
	v_fmac_f32_e32 v173, v35, v83
	v_fmac_f32_e32 v174, v35, v99
	v_fmac_f32_e32 v175, v35, v115
	v_fmac_f32_e32 v169, v35, v131
	v_fmac_f32_e32 v172, v36, v68
	v_fmac_f32_e32 v173, v36, v84
	v_fmac_f32_e32 v174, v36, v100
	v_fmac_f32_e32 v175, v36, v116
	v_fmac_f32_e32 v169, v36, v132
	v_fmac_f32_e32 v172, v37, v69
	v_fmac_f32_e32 v173, v37, v85
	v_fmac_f32_e32 v174, v37, v101
	v_fmac_f32_e32 v175, v37, v117
	v_fmac_f32_e32 v169, v37, v133
	v_fmac_f32_e32 v172, v38, v70
	v_fmac_f32_e32 v173, v38, v86
	v_fmac_f32_e32 v174, v38, v102
	v_fmac_f32_e32 v175, v38, v118
	v_fmac_f32_e32 v169, v38, v134
	v_fmac_f32_e32 v172, v39, v71
	v_fmac_f32_e32 v173, v39, v87
	v_fmac_f32_e32 v174, v39, v103
	v_fmac_f32_e32 v175, v39, v119
	v_fmac_f32_e32 v169, v39, v135
	v_fmac_f32_e32 v172, v40, v72
	v_fmac_f32_e32 v173, v40, v88
	v_fmac_f32_e32 v174, v40, v104
	v_fmac_f32_e32 v175, v40, v120
	v_fmac_f32_e32 v169, v40, v136
	v_fmac_f32_e32 v172, v41, v73
	v_fmac_f32_e32 v173, v41, v89
	v_fmac_f32_e32 v174, v41, v105
	v_fmac_f32_e32 v175, v41, v121
	v_fmac_f32_e32 v169, v41, v137
	v_fmac_f32_e32 v172, v42, v74
	v_fmac_f32_e32 v173, v42, v90
	v_fmac_f32_e32 v174, v42, v106
	v_fmac_f32_e32 v175, v42, v122
	v_fmac_f32_e32 v169, v42, v138
	v_fmac_f32_e32 v172, v43, v75
	v_fmac_f32_e32 v173, v43, v91
	v_fmac_f32_e32 v174, v43, v107
	v_fmac_f32_e32 v175, v43, v123
	v_fmac_f32_e32 v169, v43, v139
	v_fmac_f32_e32 v172, v44, v76
	v_fmac_f32_e32 v173, v44, v92
	v_fmac_f32_e32 v174, v44, v108
	v_fmac_f32_e32 v175, v44, v124
	v_fmac_f32_e32 v169, v44, v140
	v_fmac_f32_e32 v172, v45, v77
	v_fmac_f32_e32 v173, v45, v93
	v_fmac_f32_e32 v174, v45, v109
	v_fmac_f32_e32 v175, v45, v125
	v_fmac_f32_e32 v169, v45, v141
	v_fmac_f32_e32 v172, v46, v78
	v_fmac_f32_e32 v173, v46, v94
	v_fmac_f32_e32 v174, v46, v110
	v_fmac_f32_e32 v175, v46, v126
	v_fmac_f32_e32 v169, v46, v142
	v_fmac_f32_e32 v172, v47, v79
	v_fmac_f32_e32 v173, v47, v95
	v_fmac_f32_e32 v174, v47, v111
	v_fmac_f32_e32 v175, v47, v127
	v_fmac_f32_e32 v169, v47, v143
	ds_read_b128 v[64:67], v180 offset:192
	ds_read_b128 v[68:71], v180 offset:208
	ds_read_b128 v[72:75], v180 offset:224
	ds_read_b128 v[76:79], v180 offset:240
	ds_read_b128 v[80:83], v180 offset:4288
	ds_read_b128 v[84:87], v180 offset:4304
	ds_read_b128 v[88:91], v180 offset:4320
	ds_read_b128 v[92:95], v180 offset:4336
	ds_read_b128 v[96:99], v180 offset:8384
	ds_read_b128 v[100:103], v180 offset:8400
	ds_read_b128 v[104:107], v180 offset:8416
	ds_read_b128 v[108:111], v180 offset:8432
	ds_read_b128 v[112:115], v180 offset:12480
	ds_read_b128 v[116:119], v180 offset:12496
	ds_read_b128 v[120:123], v180 offset:12512
	ds_read_b128 v[124:127], v180 offset:12528
	ds_read_b128 v[128:131], v180 offset:16576
	ds_read_b128 v[132:135], v180 offset:16592
	ds_read_b128 v[136:139], v180 offset:16608
	ds_read_b128 v[140:143], v180 offset:16624
	s_waitcnt vmcnt(32)
	global_load_dword v32, v176, s[0:1]
	s_add_u32 s0, s0, 0x6000
	s_addc_u32 s1, s1, 0
	global_load_dword v33, v176, s[0:1]
	s_add_u32 s0, s0, 0x6000
	s_addc_u32 s1, s1, 0
	global_load_dword v34, v176, s[0:1]
	s_add_u32 s0, s0, 0x6000
	s_addc_u32 s1, s1, 0
	global_load_dword v35, v176, s[0:1]
	s_add_u32 s0, s0, 0x6000
	s_addc_u32 s1, s1, 0
	global_load_dword v36, v176, s[0:1]
	s_add_u32 s0, s0, 0x6000
	s_addc_u32 s1, s1, 0
	global_load_dword v37, v176, s[0:1]
	s_add_u32 s0, s0, 0x6000
	s_addc_u32 s1, s1, 0
	global_load_dword v38, v176, s[0:1]
	s_add_u32 s0, s0, 0x6000
	s_addc_u32 s1, s1, 0
	global_load_dword v39, v176, s[0:1]
	s_add_u32 s0, s0, 0x6000
	s_addc_u32 s1, s1, 0
	global_load_dword v40, v176, s[0:1]
	s_add_u32 s0, s0, 0x6000
	s_addc_u32 s1, s1, 0
	global_load_dword v41, v176, s[0:1]
	s_add_u32 s0, s0, 0x6000
	s_addc_u32 s1, s1, 0
	global_load_dword v42, v176, s[0:1]
	s_add_u32 s0, s0, 0x6000
	s_addc_u32 s1, s1, 0
	global_load_dword v43, v176, s[0:1]
	s_add_u32 s0, s0, 0x6000
	s_addc_u32 s1, s1, 0
	global_load_dword v44, v176, s[0:1]
	s_add_u32 s0, s0, 0x6000
	s_addc_u32 s1, s1, 0
	global_load_dword v45, v176, s[0:1]
	s_add_u32 s0, s0, 0x6000
	s_addc_u32 s1, s1, 0
	global_load_dword v46, v176, s[0:1]
	s_add_u32 s0, s0, 0x6000
	s_addc_u32 s1, s1, 0
	global_load_dword v47, v176, s[0:1]
	s_add_u32 s0, s0, 0x6000
	s_addc_u32 s1, s1, 0
	s_waitcnt lgkmcnt(0)
	v_fmac_f32_e32 v172, v48, v64
	v_fmac_f32_e32 v173, v48, v80
	v_fmac_f32_e32 v174, v48, v96
	v_fmac_f32_e32 v175, v48, v112
	v_fmac_f32_e32 v169, v48, v128
	v_fmac_f32_e32 v172, v49, v65
	v_fmac_f32_e32 v173, v49, v81
	v_fmac_f32_e32 v174, v49, v97
	v_fmac_f32_e32 v175, v49, v113
	v_fmac_f32_e32 v169, v49, v129
	v_fmac_f32_e32 v172, v50, v66
	v_fmac_f32_e32 v173, v50, v82
	v_fmac_f32_e32 v174, v50, v98
	v_fmac_f32_e32 v175, v50, v114
	v_fmac_f32_e32 v169, v50, v130
	v_fmac_f32_e32 v172, v51, v67
	v_fmac_f32_e32 v173, v51, v83
	v_fmac_f32_e32 v174, v51, v99
	v_fmac_f32_e32 v175, v51, v115
	v_fmac_f32_e32 v169, v51, v131
	v_fmac_f32_e32 v172, v52, v68
	v_fmac_f32_e32 v173, v52, v84
	v_fmac_f32_e32 v174, v52, v100
	v_fmac_f32_e32 v175, v52, v116
	v_fmac_f32_e32 v169, v52, v132
	v_fmac_f32_e32 v172, v53, v69
	v_fmac_f32_e32 v173, v53, v85
	v_fmac_f32_e32 v174, v53, v101
	v_fmac_f32_e32 v175, v53, v117
	v_fmac_f32_e32 v169, v53, v133
	v_fmac_f32_e32 v172, v54, v70
	v_fmac_f32_e32 v173, v54, v86
	v_fmac_f32_e32 v174, v54, v102
	v_fmac_f32_e32 v175, v54, v118
	v_fmac_f32_e32 v169, v54, v134
	v_fmac_f32_e32 v172, v55, v71
	v_fmac_f32_e32 v173, v55, v87
	v_fmac_f32_e32 v174, v55, v103
	v_fmac_f32_e32 v175, v55, v119
	v_fmac_f32_e32 v169, v55, v135
	v_fmac_f32_e32 v172, v56, v72
	v_fmac_f32_e32 v173, v56, v88
	v_fmac_f32_e32 v174, v56, v104
	v_fmac_f32_e32 v175, v56, v120
	v_fmac_f32_e32 v169, v56, v136
	v_fmac_f32_e32 v172, v57, v73
	v_fmac_f32_e32 v173, v57, v89
	v_fmac_f32_e32 v174, v57, v105
	v_fmac_f32_e32 v175, v57, v121
	v_fmac_f32_e32 v169, v57, v137
	v_fmac_f32_e32 v172, v58, v74
	v_fmac_f32_e32 v173, v58, v90
	v_fmac_f32_e32 v174, v58, v106
	v_fmac_f32_e32 v175, v58, v122
	v_fmac_f32_e32 v169, v58, v138
	v_fmac_f32_e32 v172, v59, v75
	v_fmac_f32_e32 v173, v59, v91
	v_fmac_f32_e32 v174, v59, v107
	v_fmac_f32_e32 v175, v59, v123
	v_fmac_f32_e32 v169, v59, v139
	v_fmac_f32_e32 v172, v60, v76
	v_fmac_f32_e32 v173, v60, v92
	v_fmac_f32_e32 v174, v60, v108
	v_fmac_f32_e32 v175, v60, v124
	v_fmac_f32_e32 v169, v60, v140
	v_fmac_f32_e32 v172, v61, v77
	v_fmac_f32_e32 v173, v61, v93
	v_fmac_f32_e32 v174, v61, v109
	v_fmac_f32_e32 v175, v61, v125
	v_fmac_f32_e32 v169, v61, v141
	v_fmac_f32_e32 v172, v62, v78
	v_fmac_f32_e32 v173, v62, v94
	v_fmac_f32_e32 v174, v62, v110
	v_fmac_f32_e32 v175, v62, v126
	v_fmac_f32_e32 v169, v62, v142
	v_fmac_f32_e32 v172, v63, v79
	v_fmac_f32_e32 v173, v63, v95
	v_fmac_f32_e32 v174, v63, v111
	v_fmac_f32_e32 v175, v63, v127
	v_fmac_f32_e32 v169, v63, v143
	ds_read_b128 v[64:67], v180 offset:256
	ds_read_b128 v[68:71], v180 offset:272
	ds_read_b128 v[72:75], v180 offset:288
	ds_read_b128 v[76:79], v180 offset:304
	ds_read_b128 v[80:83], v180 offset:4352
	ds_read_b128 v[84:87], v180 offset:4368
	ds_read_b128 v[88:91], v180 offset:4384
	ds_read_b128 v[92:95], v180 offset:4400
	ds_read_b128 v[96:99], v180 offset:8448
	ds_read_b128 v[100:103], v180 offset:8464
	ds_read_b128 v[104:107], v180 offset:8480
	ds_read_b128 v[108:111], v180 offset:8496
	ds_read_b128 v[112:115], v180 offset:12544
	ds_read_b128 v[116:119], v180 offset:12560
	ds_read_b128 v[120:123], v180 offset:12576
	ds_read_b128 v[124:127], v180 offset:12592
	ds_read_b128 v[128:131], v180 offset:16640
	ds_read_b128 v[132:135], v180 offset:16656
	ds_read_b128 v[136:139], v180 offset:16672
	ds_read_b128 v[140:143], v180 offset:16688
	s_waitcnt vmcnt(32)
	global_load_dword v48, v176, s[0:1]
	s_add_u32 s0, s0, 0x6000
	s_addc_u32 s1, s1, 0
	global_load_dword v49, v176, s[0:1]
	s_add_u32 s0, s0, 0x6000
	s_addc_u32 s1, s1, 0
	global_load_dword v50, v176, s[0:1]
	s_add_u32 s0, s0, 0x6000
	s_addc_u32 s1, s1, 0
	global_load_dword v51, v176, s[0:1]
	s_add_u32 s0, s0, 0x6000
	s_addc_u32 s1, s1, 0
	global_load_dword v52, v176, s[0:1]
	s_add_u32 s0, s0, 0x6000
	s_addc_u32 s1, s1, 0
	global_load_dword v53, v176, s[0:1]
	s_add_u32 s0, s0, 0x6000
	s_addc_u32 s1, s1, 0
	global_load_dword v54, v176, s[0:1]
	s_add_u32 s0, s0, 0x6000
	s_addc_u32 s1, s1, 0
	global_load_dword v55, v176, s[0:1]
	s_add_u32 s0, s0, 0x6000
	s_addc_u32 s1, s1, 0
	global_load_dword v56, v176, s[0:1]
	s_add_u32 s0, s0, 0x6000
	s_addc_u32 s1, s1, 0
	global_load_dword v57, v176, s[0:1]
	s_add_u32 s0, s0, 0x6000
	s_addc_u32 s1, s1, 0
	global_load_dword v58, v176, s[0:1]
	s_add_u32 s0, s0, 0x6000
	s_addc_u32 s1, s1, 0
	global_load_dword v59, v176, s[0:1]
	s_add_u32 s0, s0, 0x6000
	s_addc_u32 s1, s1, 0
	global_load_dword v60, v176, s[0:1]
	s_add_u32 s0, s0, 0x6000
	s_addc_u32 s1, s1, 0
	global_load_dword v61, v176, s[0:1]
	s_add_u32 s0, s0, 0x6000
	s_addc_u32 s1, s1, 0
	global_load_dword v62, v176, s[0:1]
	s_add_u32 s0, s0, 0x6000
	s_addc_u32 s1, s1, 0
	global_load_dword v63, v176, s[0:1]
	s_add_u32 s0, s0, 0x6000
	s_addc_u32 s1, s1, 0
	s_waitcnt lgkmcnt(0)
	v_fmac_f32_e32 v172, v0, v64
	v_fmac_f32_e32 v173, v0, v80
	v_fmac_f32_e32 v174, v0, v96
	v_fmac_f32_e32 v175, v0, v112
	v_fmac_f32_e32 v169, v0, v128
	v_fmac_f32_e32 v172, v1, v65
	v_fmac_f32_e32 v173, v1, v81
	v_fmac_f32_e32 v174, v1, v97
	v_fmac_f32_e32 v175, v1, v113
	v_fmac_f32_e32 v169, v1, v129
	v_fmac_f32_e32 v172, v2, v66
	v_fmac_f32_e32 v173, v2, v82
	v_fmac_f32_e32 v174, v2, v98
	v_fmac_f32_e32 v175, v2, v114
	v_fmac_f32_e32 v169, v2, v130
	v_fmac_f32_e32 v172, v3, v67
	v_fmac_f32_e32 v173, v3, v83
	v_fmac_f32_e32 v174, v3, v99
	v_fmac_f32_e32 v175, v3, v115
	v_fmac_f32_e32 v169, v3, v131
	v_fmac_f32_e32 v172, v4, v68
	v_fmac_f32_e32 v173, v4, v84
	v_fmac_f32_e32 v174, v4, v100
	v_fmac_f32_e32 v175, v4, v116
	v_fmac_f32_e32 v169, v4, v132
	v_fmac_f32_e32 v172, v5, v69
	v_fmac_f32_e32 v173, v5, v85
	v_fmac_f32_e32 v174, v5, v101
	v_fmac_f32_e32 v175, v5, v117
	v_fmac_f32_e32 v169, v5, v133
	v_fmac_f32_e32 v172, v6, v70
	v_fmac_f32_e32 v173, v6, v86
	v_fmac_f32_e32 v174, v6, v102
	v_fmac_f32_e32 v175, v6, v118
	v_fmac_f32_e32 v169, v6, v134
	v_fmac_f32_e32 v172, v7, v71
	v_fmac_f32_e32 v173, v7, v87
	v_fmac_f32_e32 v174, v7, v103
	v_fmac_f32_e32 v175, v7, v119
	v_fmac_f32_e32 v169, v7, v135
	v_fmac_f32_e32 v172, v8, v72
	v_fmac_f32_e32 v173, v8, v88
	v_fmac_f32_e32 v174, v8, v104
	v_fmac_f32_e32 v175, v8, v120
	v_fmac_f32_e32 v169, v8, v136
	v_fmac_f32_e32 v172, v9, v73
	v_fmac_f32_e32 v173, v9, v89
	v_fmac_f32_e32 v174, v9, v105
	v_fmac_f32_e32 v175, v9, v121
	v_fmac_f32_e32 v169, v9, v137
	v_fmac_f32_e32 v172, v10, v74
	v_fmac_f32_e32 v173, v10, v90
	v_fmac_f32_e32 v174, v10, v106
	v_fmac_f32_e32 v175, v10, v122
	v_fmac_f32_e32 v169, v10, v138
	v_fmac_f32_e32 v172, v11, v75
	v_fmac_f32_e32 v173, v11, v91
	v_fmac_f32_e32 v174, v11, v107
	v_fmac_f32_e32 v175, v11, v123
	v_fmac_f32_e32 v169, v11, v139
	v_fmac_f32_e32 v172, v12, v76
	v_fmac_f32_e32 v173, v12, v92
	v_fmac_f32_e32 v174, v12, v108
	v_fmac_f32_e32 v175, v12, v124
	v_fmac_f32_e32 v169, v12, v140
	v_fmac_f32_e32 v172, v13, v77
	v_fmac_f32_e32 v173, v13, v93
	v_fmac_f32_e32 v174, v13, v109
	v_fmac_f32_e32 v175, v13, v125
	v_fmac_f32_e32 v169, v13, v141
	v_fmac_f32_e32 v172, v14, v78
	v_fmac_f32_e32 v173, v14, v94
	v_fmac_f32_e32 v174, v14, v110
	v_fmac_f32_e32 v175, v14, v126
	v_fmac_f32_e32 v169, v14, v142
	v_fmac_f32_e32 v172, v15, v79
	v_fmac_f32_e32 v173, v15, v95
	v_fmac_f32_e32 v174, v15, v111
	v_fmac_f32_e32 v175, v15, v127
	v_fmac_f32_e32 v169, v15, v143
	ds_read_b128 v[64:67], v180 offset:320
	ds_read_b128 v[68:71], v180 offset:336
	ds_read_b128 v[72:75], v180 offset:352
	ds_read_b128 v[76:79], v180 offset:368
	ds_read_b128 v[80:83], v180 offset:4416
	ds_read_b128 v[84:87], v180 offset:4432
	ds_read_b128 v[88:91], v180 offset:4448
	ds_read_b128 v[92:95], v180 offset:4464
	ds_read_b128 v[96:99], v180 offset:8512
	ds_read_b128 v[100:103], v180 offset:8528
	ds_read_b128 v[104:107], v180 offset:8544
	ds_read_b128 v[108:111], v180 offset:8560
	ds_read_b128 v[112:115], v180 offset:12608
	ds_read_b128 v[116:119], v180 offset:12624
	ds_read_b128 v[120:123], v180 offset:12640
	ds_read_b128 v[124:127], v180 offset:12656
	ds_read_b128 v[128:131], v180 offset:16704
	ds_read_b128 v[132:135], v180 offset:16720
	ds_read_b128 v[136:139], v180 offset:16736
	ds_read_b128 v[140:143], v180 offset:16752
	s_waitcnt vmcnt(32)
	s_waitcnt lgkmcnt(0)
	v_fmac_f32_e32 v172, v16, v64
	v_fmac_f32_e32 v173, v16, v80
	v_fmac_f32_e32 v174, v16, v96
	v_fmac_f32_e32 v175, v16, v112
	v_fmac_f32_e32 v169, v16, v128
	v_fmac_f32_e32 v172, v17, v65
	v_fmac_f32_e32 v173, v17, v81
	v_fmac_f32_e32 v174, v17, v97
	v_fmac_f32_e32 v175, v17, v113
	v_fmac_f32_e32 v169, v17, v129
	v_fmac_f32_e32 v172, v18, v66
	v_fmac_f32_e32 v173, v18, v82
	v_fmac_f32_e32 v174, v18, v98
	v_fmac_f32_e32 v175, v18, v114
	v_fmac_f32_e32 v169, v18, v130
	v_fmac_f32_e32 v172, v19, v67
	v_fmac_f32_e32 v173, v19, v83
	v_fmac_f32_e32 v174, v19, v99
	v_fmac_f32_e32 v175, v19, v115
	v_fmac_f32_e32 v169, v19, v131
	v_fmac_f32_e32 v172, v20, v68
	v_fmac_f32_e32 v173, v20, v84
	v_fmac_f32_e32 v174, v20, v100
	v_fmac_f32_e32 v175, v20, v116
	v_fmac_f32_e32 v169, v20, v132
	v_fmac_f32_e32 v172, v21, v69
	v_fmac_f32_e32 v173, v21, v85
	v_fmac_f32_e32 v174, v21, v101
	v_fmac_f32_e32 v175, v21, v117
	v_fmac_f32_e32 v169, v21, v133
	v_fmac_f32_e32 v172, v22, v70
	v_fmac_f32_e32 v173, v22, v86
	v_fmac_f32_e32 v174, v22, v102
	v_fmac_f32_e32 v175, v22, v118
	v_fmac_f32_e32 v169, v22, v134
	v_fmac_f32_e32 v172, v23, v71
	v_fmac_f32_e32 v173, v23, v87
	v_fmac_f32_e32 v174, v23, v103
	v_fmac_f32_e32 v175, v23, v119
	v_fmac_f32_e32 v169, v23, v135
	v_fmac_f32_e32 v172, v24, v72
	v_fmac_f32_e32 v173, v24, v88
	v_fmac_f32_e32 v174, v24, v104
	v_fmac_f32_e32 v175, v24, v120
	v_fmac_f32_e32 v169, v24, v136
	v_fmac_f32_e32 v172, v25, v73
	v_fmac_f32_e32 v173, v25, v89
	v_fmac_f32_e32 v174, v25, v105
	v_fmac_f32_e32 v175, v25, v121
	v_fmac_f32_e32 v169, v25, v137
	v_fmac_f32_e32 v172, v26, v74
	v_fmac_f32_e32 v173, v26, v90
	v_fmac_f32_e32 v174, v26, v106
	v_fmac_f32_e32 v175, v26, v122
	v_fmac_f32_e32 v169, v26, v138
	v_fmac_f32_e32 v172, v27, v75
	v_fmac_f32_e32 v173, v27, v91
	v_fmac_f32_e32 v174, v27, v107
	v_fmac_f32_e32 v175, v27, v123
	v_fmac_f32_e32 v169, v27, v139
	v_fmac_f32_e32 v172, v28, v76
	v_fmac_f32_e32 v173, v28, v92
	v_fmac_f32_e32 v174, v28, v108
	v_fmac_f32_e32 v175, v28, v124
	v_fmac_f32_e32 v169, v28, v140
	v_fmac_f32_e32 v172, v29, v77
	v_fmac_f32_e32 v173, v29, v93
	v_fmac_f32_e32 v174, v29, v109
	v_fmac_f32_e32 v175, v29, v125
	v_fmac_f32_e32 v169, v29, v141
	v_fmac_f32_e32 v172, v30, v78
	v_fmac_f32_e32 v173, v30, v94
	v_fmac_f32_e32 v174, v30, v110
	v_fmac_f32_e32 v175, v30, v126
	v_fmac_f32_e32 v169, v30, v142
	v_fmac_f32_e32 v172, v31, v79
	v_fmac_f32_e32 v173, v31, v95
	v_fmac_f32_e32 v174, v31, v111
	v_fmac_f32_e32 v175, v31, v127
	v_fmac_f32_e32 v169, v31, v143
	ds_read_b128 v[64:67], v180 offset:384
	ds_read_b128 v[68:71], v180 offset:400
	ds_read_b128 v[72:75], v180 offset:416
	ds_read_b128 v[76:79], v180 offset:432
	ds_read_b128 v[80:83], v180 offset:4480
	ds_read_b128 v[84:87], v180 offset:4496
	ds_read_b128 v[88:91], v180 offset:4512
	ds_read_b128 v[92:95], v180 offset:4528
	ds_read_b128 v[96:99], v180 offset:8576
	ds_read_b128 v[100:103], v180 offset:8592
	ds_read_b128 v[104:107], v180 offset:8608
	ds_read_b128 v[108:111], v180 offset:8624
	ds_read_b128 v[112:115], v180 offset:12672
	ds_read_b128 v[116:119], v180 offset:12688
	ds_read_b128 v[120:123], v180 offset:12704
	ds_read_b128 v[124:127], v180 offset:12720
	ds_read_b128 v[128:131], v180 offset:16768
	ds_read_b128 v[132:135], v180 offset:16784
	ds_read_b128 v[136:139], v180 offset:16800
	ds_read_b128 v[140:143], v180 offset:16816
	s_waitcnt vmcnt(16)
	s_waitcnt lgkmcnt(0)
	v_fmac_f32_e32 v172, v32, v64
	v_fmac_f32_e32 v173, v32, v80
	v_fmac_f32_e32 v174, v32, v96
	v_fmac_f32_e32 v175, v32, v112
	v_fmac_f32_e32 v169, v32, v128
	v_fmac_f32_e32 v172, v33, v65
	v_fmac_f32_e32 v173, v33, v81
	v_fmac_f32_e32 v174, v33, v97
	v_fmac_f32_e32 v175, v33, v113
	v_fmac_f32_e32 v169, v33, v129
	v_fmac_f32_e32 v172, v34, v66
	v_fmac_f32_e32 v173, v34, v82
	v_fmac_f32_e32 v174, v34, v98
	v_fmac_f32_e32 v175, v34, v114
	v_fmac_f32_e32 v169, v34, v130
	v_fmac_f32_e32 v172, v35, v67
	v_fmac_f32_e32 v173, v35, v83
	v_fmac_f32_e32 v174, v35, v99
	v_fmac_f32_e32 v175, v35, v115
	v_fmac_f32_e32 v169, v35, v131
	v_fmac_f32_e32 v172, v36, v68
	v_fmac_f32_e32 v173, v36, v84
	v_fmac_f32_e32 v174, v36, v100
	v_fmac_f32_e32 v175, v36, v116
	v_fmac_f32_e32 v169, v36, v132
	v_fmac_f32_e32 v172, v37, v69
	v_fmac_f32_e32 v173, v37, v85
	v_fmac_f32_e32 v174, v37, v101
	v_fmac_f32_e32 v175, v37, v117
	v_fmac_f32_e32 v169, v37, v133
	v_fmac_f32_e32 v172, v38, v70
	v_fmac_f32_e32 v173, v38, v86
	v_fmac_f32_e32 v174, v38, v102
	v_fmac_f32_e32 v175, v38, v118
	v_fmac_f32_e32 v169, v38, v134
	v_fmac_f32_e32 v172, v39, v71
	v_fmac_f32_e32 v173, v39, v87
	v_fmac_f32_e32 v174, v39, v103
	v_fmac_f32_e32 v175, v39, v119
	v_fmac_f32_e32 v169, v39, v135
	v_fmac_f32_e32 v172, v40, v72
	v_fmac_f32_e32 v173, v40, v88
	v_fmac_f32_e32 v174, v40, v104
	v_fmac_f32_e32 v175, v40, v120
	v_fmac_f32_e32 v169, v40, v136
	v_fmac_f32_e32 v172, v41, v73
	v_fmac_f32_e32 v173, v41, v89
	v_fmac_f32_e32 v174, v41, v105
	v_fmac_f32_e32 v175, v41, v121
	v_fmac_f32_e32 v169, v41, v137
	v_fmac_f32_e32 v172, v42, v74
	v_fmac_f32_e32 v173, v42, v90
	v_fmac_f32_e32 v174, v42, v106
	v_fmac_f32_e32 v175, v42, v122
	v_fmac_f32_e32 v169, v42, v138
	v_fmac_f32_e32 v172, v43, v75
	v_fmac_f32_e32 v173, v43, v91
	v_fmac_f32_e32 v174, v43, v107
	v_fmac_f32_e32 v175, v43, v123
	v_fmac_f32_e32 v169, v43, v139
	v_fmac_f32_e32 v172, v44, v76
	v_fmac_f32_e32 v173, v44, v92
	v_fmac_f32_e32 v174, v44, v108
	v_fmac_f32_e32 v175, v44, v124
	v_fmac_f32_e32 v169, v44, v140
	v_fmac_f32_e32 v172, v45, v77
	v_fmac_f32_e32 v173, v45, v93
	v_fmac_f32_e32 v174, v45, v109
	v_fmac_f32_e32 v175, v45, v125
	v_fmac_f32_e32 v169, v45, v141
	v_fmac_f32_e32 v172, v46, v78
	v_fmac_f32_e32 v173, v46, v94
	v_fmac_f32_e32 v174, v46, v110
	v_fmac_f32_e32 v175, v46, v126
	v_fmac_f32_e32 v169, v46, v142
	v_fmac_f32_e32 v172, v47, v79
	v_fmac_f32_e32 v173, v47, v95
	v_fmac_f32_e32 v174, v47, v111
	v_fmac_f32_e32 v175, v47, v127
	v_fmac_f32_e32 v169, v47, v143
	ds_read_b128 v[64:67], v180 offset:448
	ds_read_b128 v[68:71], v180 offset:464
	ds_read_b128 v[72:75], v180 offset:480
	ds_read_b128 v[76:79], v180 offset:496
	ds_read_b128 v[80:83], v180 offset:4544
	ds_read_b128 v[84:87], v180 offset:4560
	ds_read_b128 v[88:91], v180 offset:4576
	ds_read_b128 v[92:95], v180 offset:4592
	ds_read_b128 v[96:99], v180 offset:8640
	ds_read_b128 v[100:103], v180 offset:8656
	ds_read_b128 v[104:107], v180 offset:8672
	ds_read_b128 v[108:111], v180 offset:8688
	ds_read_b128 v[112:115], v180 offset:12736
	ds_read_b128 v[116:119], v180 offset:12752
	ds_read_b128 v[120:123], v180 offset:12768
	ds_read_b128 v[124:127], v180 offset:12784
	ds_read_b128 v[128:131], v180 offset:16832
	ds_read_b128 v[132:135], v180 offset:16848
	ds_read_b128 v[136:139], v180 offset:16864
	ds_read_b128 v[140:143], v180 offset:16880
	s_waitcnt vmcnt(0)
	s_waitcnt lgkmcnt(0)
	v_fmac_f32_e32 v172, v48, v64
	v_fmac_f32_e32 v173, v48, v80
	v_fmac_f32_e32 v174, v48, v96
	v_fmac_f32_e32 v175, v48, v112
	v_fmac_f32_e32 v169, v48, v128
	v_fmac_f32_e32 v172, v49, v65
	v_fmac_f32_e32 v173, v49, v81
	v_fmac_f32_e32 v174, v49, v97
	v_fmac_f32_e32 v175, v49, v113
	v_fmac_f32_e32 v169, v49, v129
	v_fmac_f32_e32 v172, v50, v66
	v_fmac_f32_e32 v173, v50, v82
	v_fmac_f32_e32 v174, v50, v98
	v_fmac_f32_e32 v175, v50, v114
	v_fmac_f32_e32 v169, v50, v130
	v_fmac_f32_e32 v172, v51, v67
	v_fmac_f32_e32 v173, v51, v83
	v_fmac_f32_e32 v174, v51, v99
	v_fmac_f32_e32 v175, v51, v115
	v_fmac_f32_e32 v169, v51, v131
	v_fmac_f32_e32 v172, v52, v68
	v_fmac_f32_e32 v173, v52, v84
	v_fmac_f32_e32 v174, v52, v100
	v_fmac_f32_e32 v175, v52, v116
	v_fmac_f32_e32 v169, v52, v132
	v_fmac_f32_e32 v172, v53, v69
	v_fmac_f32_e32 v173, v53, v85
	v_fmac_f32_e32 v174, v53, v101
	v_fmac_f32_e32 v175, v53, v117
	v_fmac_f32_e32 v169, v53, v133
	v_fmac_f32_e32 v172, v54, v70
	v_fmac_f32_e32 v173, v54, v86
	v_fmac_f32_e32 v174, v54, v102
	v_fmac_f32_e32 v175, v54, v118
	v_fmac_f32_e32 v169, v54, v134
	v_fmac_f32_e32 v172, v55, v71
	v_fmac_f32_e32 v173, v55, v87
	v_fmac_f32_e32 v174, v55, v103
	v_fmac_f32_e32 v175, v55, v119
	v_fmac_f32_e32 v169, v55, v135
	v_fmac_f32_e32 v172, v56, v72
	v_fmac_f32_e32 v173, v56, v88
	v_fmac_f32_e32 v174, v56, v104
	v_fmac_f32_e32 v175, v56, v120
	v_fmac_f32_e32 v169, v56, v136
	v_fmac_f32_e32 v172, v57, v73
	v_fmac_f32_e32 v173, v57, v89
	v_fmac_f32_e32 v174, v57, v105
	v_fmac_f32_e32 v175, v57, v121
	v_fmac_f32_e32 v169, v57, v137
	v_fmac_f32_e32 v172, v58, v74
	v_fmac_f32_e32 v173, v58, v90
	v_fmac_f32_e32 v174, v58, v106
	v_fmac_f32_e32 v175, v58, v122
	v_fmac_f32_e32 v169, v58, v138
	v_fmac_f32_e32 v172, v59, v75
	v_fmac_f32_e32 v173, v59, v91
	v_fmac_f32_e32 v174, v59, v107
	v_fmac_f32_e32 v175, v59, v123
	v_fmac_f32_e32 v169, v59, v139
	v_fmac_f32_e32 v172, v60, v76
	v_fmac_f32_e32 v173, v60, v92
	v_fmac_f32_e32 v174, v60, v108
	v_fmac_f32_e32 v175, v60, v124
	v_fmac_f32_e32 v169, v60, v140
	v_fmac_f32_e32 v172, v61, v77
	v_fmac_f32_e32 v173, v61, v93
	v_fmac_f32_e32 v174, v61, v109
	v_fmac_f32_e32 v175, v61, v125
	v_fmac_f32_e32 v169, v61, v141
	v_fmac_f32_e32 v172, v62, v78
	v_fmac_f32_e32 v173, v62, v94
	v_fmac_f32_e32 v174, v62, v110
	v_fmac_f32_e32 v175, v62, v126
	v_fmac_f32_e32 v169, v62, v142
	v_fmac_f32_e32 v172, v63, v79
	v_fmac_f32_e32 v173, v63, v95
	v_fmac_f32_e32 v174, v63, v111
	v_fmac_f32_e32 v175, v63, v127
	v_fmac_f32_e32 v169, v63, v143
	ds_write2st64_b32 v166, v172, v173 offset0:128 offset1:129
	ds_write2st64_b32 v166, v174, v175 offset0:130 offset1:131
	ds_write_b32 v166, v169 offset:33792
	s_waitcnt lgkmcnt(0)
	s_barrier
	s_and_saveexec_b64 s[0:1], vcc
	s_cbranch_execz .LBB0_50
	s_mul_i32 s14, s63, 0x1800
	v_add_u32_e32 v0, s14, v168
	v_ashrrev_i32_e32 v1, 31, v0
	v_lshl_add_u64 v[0:1], v[0:1], 2, s[12:13]
	flat_load_dword v10, v[0:1]
	ds_read2st64_b32 v[0:1], v179 offset0:128 offset1:133
	ds_read2st64_b32 v[2:3], v179 offset0:138 offset1:143
	ds_read2st64_b32 v[4:5], v179 offset0:148 offset1:153
	ds_read2st64_b32 v[6:7], v179 offset0:158 offset1:163
	v_mad_u64_u32 v[8:9], s[14:15], s63, 5, v[162:163]
	s_waitcnt lgkmcnt(0)
	v_add_f32_e32 v0, 0, v0
	v_add_f32_e32 v0, v0, v1
	v_add_f32_e32 v0, v0, v2
	v_add_f32_e32 v0, v0, v3
	v_add_f32_e32 v0, v0, v4
	v_add_f32_e32 v0, v0, v5
	v_mad_u64_u32 v[8:9], s[14:15], v8, s49, v[168:169]
	v_add_f32_e32 v0, v0, v6
	v_ashrrev_i32_e32 v9, 31, v8
	v_add_f32_e32 v0, v0, v7
	s_waitcnt vmcnt(0)
	v_add_f32_e32 v2, v0, v10
	v_lshl_add_u64 v[0:1], v[8:9], 2, s[54:55]
	global_store_dword v[0:1], v2, off
	s_branch .LBB0_50
